# batched stat-table loads (4 sites), x->bf16 loop unrolled x8, small_gemm<1> K-loop loads batched
# speedup vs baseline: 1.0182x; 1.0182x over previous
.LBB0_138:
	s_mov_b32 s3, 0
	s_lshl_b64 s[0:1], s[2:3], 9
	v_ashrrev_i32_e32 v73, 31, v72
	v_lshl_add_u64 v[0:1], s[0:1], 0, v[72:73]
	s_mov_b64 s[0:1], 0x408000
	v_cmp_gt_u64_e32 vcc, s[0:1], v[0:1]
	s_and_saveexec_b64 s[0:1], vcc
	s_cbranch_execz .LBB0_141
	s_mov_b32 s12, s26
	s_mov_b32 s13, s3
	s_lshl_b64 s[6:7], s[12:13], 9
	s_add_u32 s8, s74, 0xfc000000
	s_addc_u32 s9, s75, -1
	s_lshl_b64 s[10:11], s[2:3], 13
	v_lshl_add_u64 v[2:3], v[72:73], 4, s[10:11]
	s_lshl_b64 s[10:11], s[12:13], 13
	s_lshl_b64 s[16:17], s[2:3], 12
	s_add_u32 s16, s24, s16
	s_addc_u32 s17, s25, s17
	v_lshl_add_u64 v[4:5], v[72:73], 3, s[16:17]
	s_mov_b64 s[16:17], 0x6248000
	v_lshl_add_u64 v[4:5], v[4:5], 0, s[16:17]
	s_lshl_b64 s[12:13], s[12:13], 12
	s_mov_b64 s[16:17], 0
	s_mov_b64 s[18:19], 0x400000
	s_mov_b64 s[20:21], 0x407fff
	s_cmpk_lg_u32 s26, 0x100
	s_cbranch_scc1 .LBB0_140
	s_mov_b32 s98, 4
.Lx8_loop:
	v_lshl_add_u64 v[132:133], s[72:73], 0, v[2:3]
	global_load_dwordx4 v[100:103], v[132:133], off
	v_lshl_add_u64 v[2:3], v[2:3], 0, s[10:11]
	v_lshl_add_u64 v[0:1], v[0:1], 0, s[6:7]
	v_lshl_add_u64 v[132:133], s[72:73], 0, v[2:3]
	global_load_dwordx4 v[104:107], v[132:133], off
	v_lshl_add_u64 v[2:3], v[2:3], 0, s[10:11]
	v_lshl_add_u64 v[0:1], v[0:1], 0, s[6:7]
	v_lshl_add_u64 v[132:133], s[72:73], 0, v[2:3]
	global_load_dwordx4 v[108:111], v[132:133], off
	v_lshl_add_u64 v[2:3], v[2:3], 0, s[10:11]
	v_lshl_add_u64 v[0:1], v[0:1], 0, s[6:7]
	v_lshl_add_u64 v[132:133], s[72:73], 0, v[2:3]
	global_load_dwordx4 v[112:115], v[132:133], off
	v_lshl_add_u64 v[2:3], v[2:3], 0, s[10:11]
	v_lshl_add_u64 v[0:1], v[0:1], 0, s[6:7]
	v_lshl_add_u64 v[132:133], s[72:73], 0, v[2:3]
	global_load_dwordx4 v[116:119], v[132:133], off
	v_lshl_add_u64 v[2:3], v[2:3], 0, s[10:11]
	v_lshl_add_u64 v[0:1], v[0:1], 0, s[6:7]
	v_lshl_add_u64 v[132:133], s[72:73], 0, v[2:3]
	global_load_dwordx4 v[120:123], v[132:133], off
	v_lshl_add_u64 v[2:3], v[2:3], 0, s[10:11]
	v_lshl_add_u64 v[0:1], v[0:1], 0, s[6:7]
	v_lshl_add_u64 v[132:133], s[72:73], 0, v[2:3]
	global_load_dwordx4 v[124:127], v[132:133], off
	v_lshl_add_u64 v[2:3], v[2:3], 0, s[10:11]
	v_lshl_add_u64 v[0:1], v[0:1], 0, s[6:7]
	v_lshl_add_u64 v[132:133], s[72:73], 0, v[2:3]
	global_load_dwordx4 v[128:131], v[132:133], off
	v_lshl_add_u64 v[2:3], v[2:3], 0, s[10:11]
	v_lshl_add_u64 v[0:1], v[0:1], 0, s[6:7]
	s_waitcnt vmcnt(7)
	v_cvt_pk_bf16_f32 v100, v100, v101
	v_cvt_pk_bf16_f32 v101, v102, v103
	global_store_dwordx2 v[4:5], v[100:101], off
	v_lshl_add_u64 v[4:5], v[4:5], 0, s[12:13]
	s_waitcnt vmcnt(7)
	v_cvt_pk_bf16_f32 v104, v104, v105
	v_cvt_pk_bf16_f32 v105, v106, v107
	global_store_dwordx2 v[4:5], v[104:105], off
	v_lshl_add_u64 v[4:5], v[4:5], 0, s[12:13]
	s_waitcnt vmcnt(7)
	v_cvt_pk_bf16_f32 v108, v108, v109
	v_cvt_pk_bf16_f32 v109, v110, v111
	global_store_dwordx2 v[4:5], v[108:109], off
	v_lshl_add_u64 v[4:5], v[4:5], 0, s[12:13]
	s_waitcnt vmcnt(7)
	v_cvt_pk_bf16_f32 v112, v112, v113
	v_cvt_pk_bf16_f32 v113, v114, v115
	global_store_dwordx2 v[4:5], v[112:113], off
	v_lshl_add_u64 v[4:5], v[4:5], 0, s[12:13]
	s_waitcnt vmcnt(7)
	v_cvt_pk_bf16_f32 v116, v116, v117
	v_cvt_pk_bf16_f32 v117, v118, v119
	global_store_dwordx2 v[4:5], v[116:117], off
	v_lshl_add_u64 v[4:5], v[4:5], 0, s[12:13]
	s_waitcnt vmcnt(7)
	v_cvt_pk_bf16_f32 v120, v120, v121
	v_cvt_pk_bf16_f32 v121, v122, v123
	global_store_dwordx2 v[4:5], v[120:121], off
	v_lshl_add_u64 v[4:5], v[4:5], 0, s[12:13]
	s_waitcnt vmcnt(7)
	v_cvt_pk_bf16_f32 v124, v124, v125
	v_cvt_pk_bf16_f32 v125, v126, v127
	global_store_dwordx2 v[4:5], v[124:125], off
	v_lshl_add_u64 v[4:5], v[4:5], 0, s[12:13]
	s_waitcnt vmcnt(7)
	v_cvt_pk_bf16_f32 v128, v128, v129
	v_cvt_pk_bf16_f32 v129, v130, v131
	global_store_dwordx2 v[4:5], v[128:129], off
	v_lshl_add_u64 v[4:5], v[4:5], 0, s[12:13]
	s_sub_u32 s98, s98, 1
	s_cmp_lg_u32 s98, 0
	s_cbranch_scc1 .Lx8_loop
	v_cmp_ge_u64_e32 vcc, s[20:21], v[0:1]
	s_and_b64 exec, exec, vcc
	s_cbranch_execz .LBB0_141

.LBB0_203:
	s_lshr_b32 s6, s4, 1
	v_writelane_b32 v255, s6, 19
	s_nop 1
	v_writelane_b32 v255, s7, 20
	v_writelane_b32 v255, s4, 21
	s_bitcmp1_b32 s4, 0
	s_nop 0
	v_writelane_b32 v255, s5, 22
	s_cselect_b64 s[4:5], -1, 0
	s_and_b64 vcc, exec, s[4:5]
	s_mov_b64 s[4:5], -1
	s_cbranch_vccz .LBB0_385
	s_mov_b64 s[4:5], s[24:25]
	s_add_u32 s6, s4, 0xc50c000
	s_addc_u32 s7, s5, 0
	s_mov_b64 s[8:9], exec
	v_readlane_b32 s10, v254, 59
	v_readlane_b32 s11, v254, 60
	s_and_b64 s[10:11], s[8:9], s[10:11]
	s_mov_b64 exec, s[10:11]
	s_cbranch_execz .LBB0_206
	v_lshl_add_u64 v[6:7], s[6:7], 0, v[198:199]
	global_load_dwordx4 v[100:103], v[6:7], off
	global_load_dwordx4 v[104:107], v[6:7], off offset:16
	global_load_dwordx4 v[108:111], v[6:7], off offset:32
	global_load_dwordx4 v[112:115], v[6:7], off offset:48
	global_load_dwordx4 v[116:119], v[6:7], off offset:64
	global_load_dwordx4 v[120:123], v[6:7], off offset:80
	global_load_dwordx4 v[124:127], v[6:7], off offset:96
	global_load_dwordx4 v[128:131], v[6:7], off offset:112
	s_mov_b32 s10, 0x3a800000
	s_waitcnt vmcnt(0) lgkmcnt(0)
	v_pk_add_f32 v[100:101], v[100:101], v[102:103]
	v_pk_add_f32 v[104:105], v[104:105], v[106:107]
	v_pk_add_f32 v[108:109], v[108:109], v[110:111]
	v_pk_add_f32 v[112:113], v[112:113], v[114:115]
	v_pk_add_f32 v[116:117], v[116:117], v[118:119]
	v_pk_add_f32 v[120:121], v[120:121], v[122:123]
	v_pk_add_f32 v[124:125], v[124:125], v[126:127]
	v_pk_add_f32 v[128:129], v[128:129], v[130:131]
	v_pk_add_f32 v[8:9], v[100:101], 0 op_sel_hi:[1,0]
	s_nop 0
	v_pk_add_f32 v[8:9], v[8:9], v[104:105]
	s_nop 0
	v_pk_add_f32 v[8:9], v[8:9], v[108:109]
	s_nop 0
	v_pk_add_f32 v[8:9], v[8:9], v[112:113]
	s_nop 0
	v_pk_add_f32 v[8:9], v[8:9], v[116:117]
	s_nop 0
	v_pk_add_f32 v[8:9], v[8:9], v[120:121]
	s_nop 0
	v_pk_add_f32 v[8:9], v[8:9], v[124:125]
	s_nop 0
	v_pk_add_f32 v[2:3], v[8:9], v[128:129]
	s_nop 0
	v_pk_mul_f32 v[2:3], v[2:3], s[10:11] op_sel_hi:[1,0]
	s_nop 0
	v_fma_f32 v1, -v2, v2, v3
	v_max_f32_e32 v1, 0, v1
	v_add_f32_e32 v1, 0x3727c5ac, v1
	v_cmp_gt_f32_e32 vcc, s78, v1
	v_mul_f32_e32 v3, 0x4b800000, v1
	s_nop 0
	v_cndmask_b32_e32 v1, v1, v3, vcc
	v_rsq_f32_e32 v1, v1
	s_nop 0
	v_mul_f32_e32 v3, 0x45800000, v1
	v_cndmask_b32_e32 v3, v1, v3, vcc
	ds_write_b64 v217, v[2:3]

.LBB0_385:
	v_readlane_b32 s68, v252, 32
	s_mov_b64 s[6:7], 0x1c00000
	s_and_b64 vcc, exec, s[4:5]
	v_readlane_b32 s72, v252, 36
	v_readlane_b32 s73, v252, 37
	v_readlane_b32 s74, v252, 38
	v_readlane_b32 s75, v252, 39
	v_readlane_b32 s76, v252, 40
	v_readlane_b32 s77, v252, 41
	v_readlane_b32 s78, v252, 42
	v_readlane_b32 s79, v252, 43
	v_readlane_b32 s80, v252, 44
	v_readlane_b32 s81, v252, 45
	v_readlane_b32 s69, v252, 33
	v_readlane_b32 s70, v252, 34
	v_readlane_b32 s71, v252, 35
	v_readlane_b32 s82, v252, 46
	v_readlane_b32 s83, v252, 47
	s_cbranch_vccz .LBB0_1088
	v_readlane_b32 s6, v255, 21
	s_cmp_eq_u32 s6, 0
	s_mov_b64 s[4:5], s[24:25]
	v_readlane_b32 s7, v255, 22
	s_cselect_b64 s[10:11], -1, 0
	s_cmp_lg_u32 s6, 0
	s_cselect_b64 s[6:7], -1, 0
	s_add_u32 s8, s4, 0xc50c000
	v_readlane_b32 s70, v253, 53
	s_addc_u32 s9, s5, 0
	s_and_b64 vcc, exec, s[10:11]
	v_readlane_b32 s71, v253, 54
	v_readlane_b32 s82, v255, 15
	s_mov_b32 s83, 0x800000
	s_cbranch_vccnz .LBB0_390
	s_mov_b64 s[12:13], exec
	v_readlane_b32 s14, v254, 59
	v_readlane_b32 s15, v254, 60
	s_and_b64 s[14:15], s[12:13], s[14:15]
	s_mov_b64 exec, s[14:15]
	s_cbranch_execz .LBB0_389
	v_lshl_add_u64 v[6:7], s[8:9], 0, v[198:199]
	global_load_dwordx4 v[100:103], v[6:7], off
	global_load_dwordx4 v[104:107], v[6:7], off offset:16
	global_load_dwordx4 v[108:111], v[6:7], off offset:32
	global_load_dwordx4 v[112:115], v[6:7], off offset:48
	global_load_dwordx4 v[116:119], v[6:7], off offset:64
	global_load_dwordx4 v[120:123], v[6:7], off offset:80
	global_load_dwordx4 v[124:127], v[6:7], off offset:96
	global_load_dwordx4 v[128:131], v[6:7], off offset:112
	s_mov_b32 s14, 0x3a800000
	s_waitcnt vmcnt(0) lgkmcnt(0)
	v_pk_add_f32 v[100:101], v[100:101], v[102:103]
	v_pk_add_f32 v[104:105], v[104:105], v[106:107]
	v_pk_add_f32 v[108:109], v[108:109], v[110:111]
	v_pk_add_f32 v[112:113], v[112:113], v[114:115]
	v_pk_add_f32 v[116:117], v[116:117], v[118:119]
	v_pk_add_f32 v[120:121], v[120:121], v[122:123]
	v_pk_add_f32 v[124:125], v[124:125], v[126:127]
	v_pk_add_f32 v[128:129], v[128:129], v[130:131]
	v_pk_add_f32 v[8:9], v[100:101], 0 op_sel_hi:[1,0]
	s_nop 0
	v_pk_add_f32 v[8:9], v[8:9], v[104:105]
	s_nop 0
	v_pk_add_f32 v[8:9], v[8:9], v[108:109]
	s_nop 0
	v_pk_add_f32 v[8:9], v[8:9], v[112:113]
	s_nop 0
	v_pk_add_f32 v[8:9], v[8:9], v[116:117]
	s_nop 0
	v_pk_add_f32 v[8:9], v[8:9], v[120:121]
	s_nop 0
	v_pk_add_f32 v[8:9], v[8:9], v[124:125]
	s_nop 0
	v_pk_add_f32 v[2:3], v[8:9], v[128:129]
	s_nop 0
	v_pk_mul_f32 v[2:3], v[2:3], s[14:15] op_sel_hi:[1,0]
	s_nop 0
	v_fma_f32 v1, -v2, v2, v3
	v_max_f32_e32 v1, 0, v1
	v_add_f32_e32 v1, 0x3727c5ac, v1
	v_cmp_gt_f32_e32 vcc, s83, v1
	v_mul_f32_e32 v3, 0x4b800000, v1
	s_nop 0
	v_cndmask_b32_e32 v1, v1, v3, vcc
	v_rsq_f32_e32 v1, v1
	s_nop 0
	v_mul_f32_e32 v3, 0x45800000, v1
	v_cndmask_b32_e32 v3, v1, v3, vcc
	ds_write_b64 v217, v[2:3]

.LBB0_1091:
	s_andn2_b64 vcc, exec, s[4:5]
	s_cbranch_vccnz .LBB0_1158
	s_mov_b64 s[28:29], s[24:25]
	s_add_u32 s42, s28, 0xc308000
	s_addc_u32 s43, s29, 0
	s_mov_b64 s[4:5], exec
	v_readlane_b32 s36, v254, 59
	v_readlane_b32 s37, v254, 60
	s_and_b64 s[36:37], s[4:5], s[36:37]
	s_mov_b64 exec, s[36:37]
	s_cbranch_execz .LBB0_1094
	v_lshl_add_u64 v[6:7], s[42:43], 0, v[198:199]
	global_load_dwordx4 v[100:103], v[6:7], off
	global_load_dwordx4 v[104:107], v[6:7], off offset:16
	global_load_dwordx4 v[108:111], v[6:7], off offset:32
	global_load_dwordx4 v[112:115], v[6:7], off offset:48
	global_load_dwordx4 v[116:119], v[6:7], off offset:64
	global_load_dwordx4 v[120:123], v[6:7], off offset:80
	global_load_dwordx4 v[124:127], v[6:7], off offset:96
	global_load_dwordx4 v[128:131], v[6:7], off offset:112
	s_mov_b32 s36, 0x3a800000
	s_waitcnt vmcnt(0) lgkmcnt(0)
	v_pk_add_f32 v[100:101], v[100:101], v[102:103]
	v_pk_add_f32 v[104:105], v[104:105], v[106:107]
	v_pk_add_f32 v[108:109], v[108:109], v[110:111]
	v_pk_add_f32 v[112:113], v[112:113], v[114:115]
	v_pk_add_f32 v[116:117], v[116:117], v[118:119]
	v_pk_add_f32 v[120:121], v[120:121], v[122:123]
	v_pk_add_f32 v[124:125], v[124:125], v[126:127]
	v_pk_add_f32 v[128:129], v[128:129], v[130:131]
	v_pk_add_f32 v[8:9], v[100:101], 0 op_sel_hi:[1,0]
	s_nop 0
	v_pk_add_f32 v[8:9], v[8:9], v[104:105]
	s_nop 0
	v_pk_add_f32 v[8:9], v[8:9], v[108:109]
	s_nop 0
	v_pk_add_f32 v[8:9], v[8:9], v[112:113]
	s_nop 0
	v_pk_add_f32 v[8:9], v[8:9], v[116:117]
	s_nop 0
	v_pk_add_f32 v[8:9], v[8:9], v[120:121]
	s_nop 0
	v_pk_add_f32 v[8:9], v[8:9], v[124:125]
	s_nop 0
	v_pk_add_f32 v[2:3], v[8:9], v[128:129]
	s_nop 0
	v_pk_mul_f32 v[2:3], v[2:3], s[36:37] op_sel_hi:[1,0]
	s_nop 0
	v_fma_f32 v1, -v2, v2, v3
	v_max_f32_e32 v1, 0, v1
	v_add_f32_e32 v1, 0x3727c5ac, v1
	v_cmp_gt_f32_e32 vcc, s78, v1
	v_mul_f32_e32 v3, 0x4b800000, v1
	s_nop 0
	v_cndmask_b32_e32 v1, v1, v3, vcc
	v_rsq_f32_e32 v1, v1
	s_nop 0
	v_mul_f32_e32 v3, 0x45800000, v1
	v_cndmask_b32_e32 v3, v1, v3, vcc
	ds_write_b64 v217, v[2:3]

.LBB0_1166:
	s_mov_b64 s[40:41], exec
	v_readlane_b32 s42, v254, 59
	v_readlane_b32 s43, v254, 60
	s_and_b64 s[42:43], s[40:41], s[42:43]
	s_mov_b64 exec, s[42:43]
	s_cbranch_execz .LBB0_1168
	s_waitcnt vmcnt(0)
	v_lshl_add_u64 v[6:7], s[50:51], 0, v[198:199]
	global_load_dwordx4 v[100:103], v[6:7], off
	global_load_dwordx4 v[104:107], v[6:7], off offset:16
	global_load_dwordx4 v[108:111], v[6:7], off offset:32
	global_load_dwordx4 v[112:115], v[6:7], off offset:48
	global_load_dwordx4 v[116:119], v[6:7], off offset:64
	global_load_dwordx4 v[120:123], v[6:7], off offset:80
	global_load_dwordx4 v[124:127], v[6:7], off offset:96
	global_load_dwordx4 v[128:131], v[6:7], off offset:112
	s_mov_b32 s38, 0x3a800000
	s_waitcnt vmcnt(0) lgkmcnt(0)
	v_pk_add_f32 v[100:101], v[100:101], v[102:103]
	v_pk_add_f32 v[104:105], v[104:105], v[106:107]
	v_pk_add_f32 v[108:109], v[108:109], v[110:111]
	v_pk_add_f32 v[112:113], v[112:113], v[114:115]
	v_pk_add_f32 v[116:117], v[116:117], v[118:119]
	v_pk_add_f32 v[120:121], v[120:121], v[122:123]
	v_pk_add_f32 v[124:125], v[124:125], v[126:127]
	v_pk_add_f32 v[128:129], v[128:129], v[130:131]
	v_pk_add_f32 v[8:9], v[100:101], 0 op_sel_hi:[1,0]
	s_nop 0
	v_pk_add_f32 v[8:9], v[8:9], v[104:105]
	s_nop 0
	v_pk_add_f32 v[8:9], v[8:9], v[108:109]
	s_nop 0
	v_pk_add_f32 v[8:9], v[8:9], v[112:113]
	s_nop 0
	v_pk_add_f32 v[8:9], v[8:9], v[116:117]
	s_nop 0
	v_pk_add_f32 v[8:9], v[8:9], v[120:121]
	s_nop 0
	v_pk_add_f32 v[8:9], v[8:9], v[124:125]
	s_nop 0
	v_pk_add_f32 v[2:3], v[8:9], v[128:129]
	s_nop 0
	v_pk_mul_f32 v[2:3], v[2:3], s[38:39] op_sel_hi:[1,0]
	s_nop 0
	v_fma_f32 v1, -v2, v2, v3
	v_max_f32_e32 v1, 0, v1
	v_add_f32_e32 v1, 0x3727c5ac, v1
	v_cmp_gt_f32_e32 vcc, s78, v1
	v_mul_f32_e32 v3, 0x4b800000, v1
	s_nop 0
	v_cndmask_b32_e32 v1, v1, v3, vcc
	v_rsq_f32_e32 v1, v1
	s_nop 0
	v_mul_f32_e32 v3, 0x45800000, v1
	v_cndmask_b32_e32 v3, v1, v3, vcc
	ds_write_b64 v217, v[2:3]

.LBB0_1229:
	s_lshl_b32 s29, s36, 4
	s_and_b32 s37, s29, 0xffffffc0
	v_or_b32_e32 v100, s37, v135
	v_ashrrev_i32_e32 v101, 31, v100
	v_lshlrev_b64 v[102:103], 11, v[42:43]
	v_lshlrev_b64 v[38:39], 2, v[100:101]
	v_lshl_add_u64 v[42:43], s[48:49], 0, v[102:103]
	v_lshl_add_u64 v[34:35], s[52:53], 0, v[38:39]
	v_lshl_add_u64 v[38:39], s[54:55], 0, v[38:39]
	v_lshl_add_u64 v[42:43], v[100:101], 1, v[42:43]
	flat_load_dwordx4 v[34:37], v[34:35]
	v_or_b32_e32 v2, s28, v1
	flat_load_dwordx4 v[38:41], v[38:39]
	v_mul_u32_u24_e32 v2, s75, v2
	flat_load_dwordx2 v[120:121], v[42:43]
	v_or_b32_e32 v42, s37, v136
	v_ashrrev_i32_e32 v43, 31, v42
	v_or_b32_e32 v4, s37, v1
	v_lshl_add_u64 v[44:45], v[42:43], 1, 32
	v_mad_i64_i32 v[124:125], s[28:29], s27, v42, v[76:77]
	v_lshl_or_b32 v8, v4, 1, 32
	v_lshlrev_b32_e32 v42, 1, v2
	v_mov_b32_e32 v43, v0
	v_mad_u64_u32 v[122:123], s[28:29], s75, v44, v[76:77]
	v_ashrrev_i32_e32 v6, 31, v4
	v_mad_u64_u32 v[126:127], s[28:29], s75, v8, v[76:77]
	v_mad_i64_i32 v[128:129], s[28:29], s27, v4, v[76:77]
	v_lshl_add_u64 v[130:131], v[78:79], 0, v[42:43]
	v_lshl_add_u64 v[132:133], v[80:81], 0, v[42:43]
	v_mov_b32_e32 v42, 0
	v_mad_i32_i24 v123, s75, v45, v123
	v_mad_i32_i24 v127, s75, v6, v127
	s_mov_b32 s28, 0
	v_mov_b32_e32 v43, v42
	v_mov_b32_e32 v44, v42
	v_mov_b32_e32 v45, v42
	v_mov_b32_e32 v46, v42
	v_mov_b32_e32 v47, v42
	v_mov_b32_e32 v48, v42
	v_mov_b32_e32 v49, v42
	v_mov_b32_e32 v50, v42
	v_mov_b32_e32 v51, v42
	v_mov_b32_e32 v52, v42
	v_mov_b32_e32 v53, v42
	v_mov_b32_e32 v54, v42
	v_mov_b32_e32 v55, v42
	v_mov_b32_e32 v56, v42
	v_mov_b32_e32 v57, v42
	v_mov_b32_e32 v58, v42
	v_mov_b32_e32 v59, v42
	v_mov_b32_e32 v60, v42
	v_mov_b32_e32 v61, v42
	v_mov_b32_e32 v62, v42
	v_mov_b32_e32 v63, v42
	v_mov_b32_e32 v64, v42
	v_mov_b32_e32 v65, v42
	v_mov_b32_e32 v66, v42
	v_mov_b32_e32 v67, v42
	v_mov_b32_e32 v68, v42
	v_mov_b32_e32 v69, v42
	v_mov_b32_e32 v70, v42
	v_mov_b32_e32 v71, v42
	v_mov_b32_e32 v72, v42
	v_mov_b32_e32 v73, v42
	v_lshl_add_u64 v[122:123], v[122:123], 0, v[74:75]
	v_lshl_add_u64 v[124:125], v[124:125], 0, v[74:75]
	v_lshl_add_u64 v[126:127], v[126:127], 0, v[74:75]
	v_lshl_add_u64 v[128:129], v[128:129], 0, v[74:75]
	v_lshl_add_u64 v[130:131], v[130:131], 0, v[74:75]
	v_lshl_add_u64 v[132:133], v[132:133], 0, v[74:75]
	s_mov_b64 s[100:101], 0xc0
.LBB0_1230:
	global_load_dwordx4 v[140:143], v[128:129], off
	global_load_dwordx4 v[144:147], v[132:133], off
	global_load_dwordx4 v[148:151], v[126:127], off
	global_load_dwordx4 v[152:155], v[130:131], off
	global_load_dwordx4 v[156:159], v[124:125], off
	global_load_dwordx4 v[160:163], v[122:123], off
	s_add_u32 s98, s28, 32
	s_cmp_ge_u32 s98, s3
	s_cbranch_scc1 .Lsg1_ld_done
	global_load_dwordx4 v[164:167], v[128:129], off offset:64
	global_load_dwordx4 v[168:171], v[132:133], off offset:64
	global_load_dwordx4 v[172:175], v[126:127], off offset:64
	global_load_dwordx4 v[176:179], v[130:131], off offset:64
	global_load_dwordx4 v[180:183], v[124:125], off offset:64
	global_load_dwordx4 v[184:187], v[122:123], off offset:64
	s_add_u32 s98, s28, 64
	s_cmp_ge_u32 s98, s3
	s_cbranch_scc1 .Lsg1_ld_done
	global_load_dwordx4 v[188:191], v[128:129], off offset:128
	global_load_dwordx4 v[200:203], v[132:133], off offset:128
	global_load_dwordx4 v[204:207], v[126:127], off offset:128
	global_load_dwordx4 v[208:211], v[130:131], off offset:128
	global_load_dwordx4 v[222:225], v[124:125], off offset:128
	global_load_dwordx4 v[226:229], v[122:123], off offset:128
.Lsg1_ld_done:
	s_waitcnt vmcnt(0) lgkmcnt(0)
	v_mfma_f32_16x16x32_bf16 v[70:73], v[140:143], v[144:147], v[70:73]
	v_mfma_f32_16x16x32_bf16 v[62:65], v[140:143], v[152:155], v[62:65]
	v_mfma_f32_16x16x32_bf16 v[66:69], v[148:151], v[144:147], v[66:69]
	v_mfma_f32_16x16x32_bf16 v[58:61], v[148:151], v[152:155], v[58:61]
	v_mfma_f32_16x16x32_bf16 v[54:57], v[156:159], v[144:147], v[54:57]
	v_mfma_f32_16x16x32_bf16 v[50:53], v[160:163], v[144:147], v[50:53]
	v_mfma_f32_16x16x32_bf16 v[46:49], v[156:159], v[152:155], v[46:49]
	v_mfma_f32_16x16x32_bf16 v[42:45], v[160:163], v[152:155], v[42:45]
	s_add_u32 s98, s28, 32
	s_cmp_ge_u32 s98, s3
	s_cbranch_scc1 .Lsg1_mm_done
	v_mfma_f32_16x16x32_bf16 v[70:73], v[164:167], v[168:171], v[70:73]
	v_mfma_f32_16x16x32_bf16 v[62:65], v[164:167], v[176:179], v[62:65]
	v_mfma_f32_16x16x32_bf16 v[66:69], v[172:175], v[168:171], v[66:69]
	v_mfma_f32_16x16x32_bf16 v[58:61], v[172:175], v[176:179], v[58:61]
	v_mfma_f32_16x16x32_bf16 v[54:57], v[180:183], v[168:171], v[54:57]
	v_mfma_f32_16x16x32_bf16 v[50:53], v[184:187], v[168:171], v[50:53]
	v_mfma_f32_16x16x32_bf16 v[46:49], v[180:183], v[176:179], v[46:49]
	v_mfma_f32_16x16x32_bf16 v[42:45], v[184:187], v[176:179], v[42:45]
	s_add_u32 s98, s28, 64
	s_cmp_ge_u32 s98, s3
	s_cbranch_scc1 .Lsg1_mm_done
	v_mfma_f32_16x16x32_bf16 v[70:73], v[188:191], v[200:203], v[70:73]
	v_mfma_f32_16x16x32_bf16 v[62:65], v[188:191], v[208:211], v[62:65]
	v_mfma_f32_16x16x32_bf16 v[66:69], v[204:207], v[200:203], v[66:69]
	v_mfma_f32_16x16x32_bf16 v[58:61], v[204:207], v[208:211], v[58:61]
	v_mfma_f32_16x16x32_bf16 v[54:57], v[222:225], v[200:203], v[54:57]
	v_mfma_f32_16x16x32_bf16 v[50:53], v[226:229], v[200:203], v[50:53]
	v_mfma_f32_16x16x32_bf16 v[46:49], v[222:225], v[208:211], v[46:49]
	v_mfma_f32_16x16x32_bf16 v[42:45], v[226:229], v[208:211], v[42:45]
.Lsg1_mm_done:
	s_addk_i32 s28, 0x60
	v_lshl_add_u64 v[122:123], v[122:123], 0, s[100:101]
	v_lshl_add_u64 v[124:125], v[124:125], 0, s[100:101]
	v_lshl_add_u64 v[126:127], v[126:127], 0, s[100:101]
	v_lshl_add_u64 v[128:129], v[128:129], 0, s[100:101]
	v_lshl_add_u64 v[130:131], v[130:131], 0, s[100:101]
	v_lshl_add_u64 v[132:133], v[132:133], 0, s[100:101]
	s_cmp_ge_u32 s28, s3
	s_cbranch_scc0 .LBB0_1230
	s_and_b64 vcc, exec, s[56:57]
	ds_write_b128 v137, v[70:73]
	ds_write_b128 v137, v[66:69] offset:16
	ds_write_b128 v137, v[62:65] offset:2048
	ds_write_b128 v137, v[58:61] offset:2064
	ds_write_b128 v137, v[54:57] offset:4096
	ds_write_b128 v137, v[50:53] offset:4112
	ds_write_b128 v137, v[46:49] offset:6144
	ds_write_b128 v137, v[42:45] offset:6160
	s_waitcnt lgkmcnt(0)
	s_barrier
	s_cbranch_vccz .LBB0_1233
	v_pk_add_f32 v[42:43], v[116:117], v[118:119]
	v_add_f32_e32 v44, v33, v31
	v_mov_b32_e32 v45, v43
	v_add_f32_e32 v46, v29, v27
	v_pk_add_f32 v[48:49], v[112:113], v[114:115]
	v_pk_add_f32 v[44:45], v[44:45], 0 op_sel_hi:[1,0]
	v_mov_b32_e32 v47, v42
	v_add_f32_e32 v50, v25, v23
	v_pk_add_f32 v[42:43], v[46:47], v[44:45]
	v_mov_b32_e32 v51, v49
	v_add_f32_e32 v52, v21, v19
	v_pk_add_f32 v[54:55], v[108:109], v[110:111]
	v_pk_add_f32 v[42:43], v[50:51], v[42:43]
	v_mov_b32_e32 v53, v48
	v_add_f32_e32 v56, v17, v15
	v_pk_add_f32 v[42:43], v[52:53], v[42:43]
	v_mov_b32_e32 v57, v55
	v_add_f32_e32 v58, v13, v11
	v_pk_add_f32 v[60:61], v[104:105], v[106:107]
	v_pk_add_f32 v[42:43], v[56:57], v[42:43]
	v_mov_b32_e32 v59, v54
	v_add_f32_e32 v62, v9, v7
	v_pk_add_f32 v[42:43], v[58:59], v[42:43]
	v_mov_b32_e32 v63, v61
	v_add_f32_e32 v64, v5, v3
	v_pk_add_f32 v[42:43], v[62:63], v[42:43]
	v_mov_b32_e32 v65, v60
	v_pk_add_f32 v[42:43], v[64:65], v[42:43]
	s_mov_b32 s28, 0x3a800000
	v_pk_mul_f32 v[42:43], v[42:43], s[28:29] op_sel_hi:[1,0]
	s_nop 0
	v_fma_f32 v2, -v43, v43, v42
	v_max_f32_e32 v2, 0, v2
	v_add_f32_e32 v2, 0x3727c5ac, v2
	v_mul_f32_e32 v4, 0x4b800000, v2
	v_cmp_gt_f32_e32 vcc, s78, v2
	s_nop 1
	v_cndmask_b32_e32 v2, v2, v4, vcc
	v_rsq_f32_e32 v2, v2
	s_nop 0
	v_mul_f32_e32 v4, 0x45800000, v2
	v_cndmask_b32_e32 v2, v2, v4, vcc
	s_branch .LBB0_1234

	.amdhsa_kernel _Z19hgrn2_chunkmlp_mega6Params
		.amdhsa_group_segment_fixed_size 0
		.amdhsa_private_segment_fixed_size 0
		.amdhsa_kernarg_size 424
		.amdhsa_user_sgpr_count 2
		.amdhsa_user_sgpr_dispatch_ptr 0
		.amdhsa_user_sgpr_queue_ptr 0
		.amdhsa_user_sgpr_kernarg_segment_ptr 1
		.amdhsa_user_sgpr_dispatch_id 0
		.amdhsa_user_sgpr_kernarg_preload_length 0
		.amdhsa_user_sgpr_kernarg_preload_offset 0
		.amdhsa_user_sgpr_private_segment_size 0
		.amdhsa_uses_dynamic_stack 0
		.amdhsa_enable_private_segment 0
		.amdhsa_system_sgpr_workgroup_id_x 1
		.amdhsa_system_sgpr_workgroup_id_y 0
		.amdhsa_system_sgpr_workgroup_id_z 0
		.amdhsa_system_sgpr_workgroup_info 0
		.amdhsa_system_vgpr_workitem_id 2
		.amdhsa_next_free_vgpr 256
		.amdhsa_next_free_sgpr 102
		.amdhsa_accum_offset 256
		.amdhsa_reserve_vcc 1
		.amdhsa_float_round_mode_32 0
		.amdhsa_float_round_mode_16_64 0
		.amdhsa_float_denorm_mode_32 3
		.amdhsa_float_denorm_mode_16_64 3
		.amdhsa_dx10_clamp 1
		.amdhsa_ieee_mode 1
		.amdhsa_fp16_overflow 0
		.amdhsa_tg_split 0
		.amdhsa_exception_fp_ieee_invalid_op 0
		.amdhsa_exception_fp_denorm_src 0
		.amdhsa_exception_fp_ieee_div_zero 0
		.amdhsa_exception_fp_ieee_overflow 0
		.amdhsa_exception_fp_ieee_underflow 0
		.amdhsa_exception_fp_ieee_inexact 0
		.amdhsa_exception_int_div_zero 0
	.end_amdhsa_kernel

amdhsa.kernels:
  - .agpr_count:     0
    .args:
      - .offset:         0
        .size:           168
        .value_kind:     by_value
      - .offset:         168
        .size:           4
        .value_kind:     hidden_block_count_x
      - .offset:         172
        .size:           4
        .value_kind:     hidden_block_count_y
      - .offset:         176
        .size:           4
        .value_kind:     hidden_block_count_z
      - .offset:         180
        .size:           2
        .value_kind:     hidden_group_size_x
      - .offset:         182
        .size:           2
        .value_kind:     hidden_group_size_y
      - .offset:         184
        .size:           2
        .value_kind:     hidden_group_size_z
      - .offset:         186
        .size:           2
        .value_kind:     hidden_remainder_x
      - .offset:         188
        .size:           2
        .value_kind:     hidden_remainder_y
      - .offset:         190
        .size:           2
        .value_kind:     hidden_remainder_z
      - .offset:         208
        .size:           8
        .value_kind:     hidden_global_offset_x
      - .offset:         216
        .size:           8
        .value_kind:     hidden_global_offset_y
      - .offset:         224
        .size:           8
        .value_kind:     hidden_global_offset_z
      - .offset:         232
        .size:           2
        .value_kind:     hidden_grid_dims
      - .offset:         256
        .size:           8
        .value_kind:     hidden_multigrid_sync_arg
      - .offset:         288
        .size:           4
        .value_kind:     hidden_dynamic_lds_size
    .group_segment_fixed_size: 0
    .kernarg_segment_align: 8
    .kernarg_segment_size: 424
    .language:       OpenCL C
    .language_version:
      - 2
      - 0
    .max_flat_workgroup_size: 512
    .name:           _Z19hgrn2_chunkmlp_mega6Params
    .private_segment_fixed_size: 0
    .sgpr_count:     108
    .sgpr_spill_count: 245
    .symbol:         _Z19hgrn2_chunkmlp_mega6Params.kd
    .uniform_work_group_size: 1
    .uses_dynamic_stack: false
    .vgpr_count:     256
    .vgpr_spill_count: 0
    .wavefront_size: 64
